# v36 + phase-0 WA pre-composition de-serialised: 46 w_pa row loads in flight, coefficients broadcast by v_readlane (was 8 serial load batches)
# baseline (speedup 1.0000x reference)
.LBB0_15:
	s_load_dwordx16 s[52:67], s[0:1], 0x40
	v_ashrrev_i32_e32 v2, 8, v13
	v_ashrrev_i32_e32 v3, 31, v2
	v_lshlrev_b64 v[4:5], 9, v[2:3]
	v_and_b32_e32 v2, 0xffffff80, v2
	s_waitcnt lgkmcnt(0)
	s_mov_b64 s[52:53], s[56:57]
	s_mov_b64 s[54:55], s[58:59]
	s_mov_b64 s[56:57], s[60:61]
	s_mov_b64 s[58:59], s[62:63]
	s_mov_b64 s[60:61], s[64:65]
	v_ashrrev_i32_e32 v3, 31, v2
	v_lshlrev_b32_e32 v8, 2, v12
	v_lshl_add_u64 v[6:7], v[2:3], 2, s[60:61]
	v_lshlrev_b64 v[2:3], 12, v[2:3]
	s_movk_i32 s2, 0xff0
	v_and_or_b32 v2, v8, s2, v2
	v_mov_b32_e32 v8, 0
	v_lshl_add_u64 v[4:5], s[58:59], 0, v[4:5]
	v_mov_b32_e32 v10, v2
	v_mov_b32_e32 v9, v8
	v_mov_b32_e32 v2, v8
	v_mov_b32_e32 v3, v8
	s_mov_b64 s[62:63], s[66:67]
	v_readfirstlane_b32 s4, v4
	v_readfirstlane_b32 s5, v5
	v_readfirstlane_b32 s64, v6
	v_readfirstlane_b32 s65, v7
	s_mov_b64 s[66:67], exec
	s_mov_b64 exec, -1
	v_mbcnt_lo_u32_b32 v11, -1, 0
	v_mbcnt_hi_u32_b32 v11, -1, v11
	v_lshlrev_b32_e32 v11, 2, v11
	s_nop 1
	global_load_dword v192, v11, s[4:5]
	global_load_dword v193, v11, s[4:5] offset:256
	global_load_dword v254, v11, s[64:65]
	global_load_dword v255, v11, s[64:65] offset:256
	s_mov_b64 exec, s[66:67]
	s_add_u32 s98, s30, 0xffff2000
	s_addc_u32 s99, s31, -1
	global_load_dwordx4 v[14:17], v10, s[98:99] offset:-4096
	global_load_dwordx4 v[18:21], v10, s[98:99]
	s_add_u32 s98, s98, 0x2000
	s_addc_u32 s99, s99, 0
	global_load_dwordx4 v[22:25], v10, s[98:99] offset:-4096
	global_load_dwordx4 v[26:29], v10, s[98:99]
	s_add_u32 s98, s98, 0x2000
	s_addc_u32 s99, s99, 0
	global_load_dwordx4 v[30:33], v10, s[98:99] offset:-4096
	global_load_dwordx4 v[34:37], v10, s[98:99]
	s_add_u32 s98, s98, 0x2000
	s_addc_u32 s99, s99, 0
	global_load_dwordx4 v[38:41], v10, s[98:99] offset:-4096
	global_load_dwordx4 v[42:45], v10, s[98:99]
	s_add_u32 s98, s98, 0x2000
	s_addc_u32 s99, s99, 0
	global_load_dwordx4 v[46:49], v10, s[98:99] offset:-4096
	global_load_dwordx4 v[50:53], v10, s[98:99]
	s_add_u32 s98, s98, 0x2000
	s_addc_u32 s99, s99, 0
	global_load_dwordx4 v[54:57], v10, s[98:99] offset:-4096
	global_load_dwordx4 v[58:61], v10, s[98:99]
	s_add_u32 s98, s98, 0x2000
	s_addc_u32 s99, s99, 0
	global_load_dwordx4 v[62:65], v10, s[98:99] offset:-4096
	global_load_dwordx4 v[112:115], v10, s[98:99]
	s_add_u32 s98, s98, 0x2000
	s_addc_u32 s99, s99, 0
	global_load_dwordx4 v[116:119], v10, s[98:99] offset:-4096
	global_load_dwordx4 v[120:123], v10, s[98:99]
	s_add_u32 s98, s98, 0x2000
	s_addc_u32 s99, s99, 0
	global_load_dwordx4 v[124:127], v10, s[98:99] offset:-4096
	global_load_dwordx4 v[128:131], v10, s[98:99]
	s_add_u32 s98, s98, 0x2000
	s_addc_u32 s99, s99, 0
	global_load_dwordx4 v[132:135], v10, s[98:99] offset:-4096
	global_load_dwordx4 v[136:139], v10, s[98:99]
	s_add_u32 s98, s98, 0x2000
	s_addc_u32 s99, s99, 0
	global_load_dwordx4 v[140:143], v10, s[98:99] offset:-4096
	global_load_dwordx4 v[144:147], v10, s[98:99]
	s_add_u32 s98, s98, 0x2000
	s_addc_u32 s99, s99, 0
	global_load_dwordx4 v[148:151], v10, s[98:99] offset:-4096
	global_load_dwordx4 v[152:155], v10, s[98:99]
	s_add_u32 s98, s98, 0x2000
	s_addc_u32 s99, s99, 0
	global_load_dwordx4 v[156:159], v10, s[98:99] offset:-4096
	global_load_dwordx4 v[160:163], v10, s[98:99]
	s_add_u32 s98, s98, 0x2000
	s_addc_u32 s99, s99, 0
	global_load_dwordx4 v[164:167], v10, s[98:99] offset:-4096
	global_load_dwordx4 v[168:171], v10, s[98:99]
	s_add_u32 s98, s98, 0x2000
	s_addc_u32 s99, s99, 0
	global_load_dwordx4 v[172:175], v10, s[98:99] offset:-4096
	global_load_dwordx4 v[176:179], v10, s[98:99]
	s_add_u32 s98, s98, 0x2000
	s_addc_u32 s99, s99, 0
	global_load_dwordx4 v[180:183], v10, s[98:99] offset:-4096
	global_load_dwordx4 v[184:187], v10, s[98:99]
	s_add_u32 s98, s98, 0x2000
	s_addc_u32 s99, s99, 0
	global_load_dwordx4 v[188:191], v10, s[98:99] offset:-4096
	global_load_dwordx4 v[198:201], v10, s[98:99]
	s_add_u32 s98, s98, 0x2000
	s_addc_u32 s99, s99, 0
	global_load_dwordx4 v[202:205], v10, s[98:99] offset:-4096
	global_load_dwordx4 v[206:209], v10, s[98:99]
	s_add_u32 s98, s98, 0x2000
	s_addc_u32 s99, s99, 0
	global_load_dwordx4 v[212:215], v10, s[98:99] offset:-4096
	global_load_dwordx4 v[216:219], v10, s[98:99]
	s_add_u32 s98, s98, 0x2000
	s_addc_u32 s99, s99, 0
	global_load_dwordx4 v[220:223], v10, s[98:99] offset:-4096
	global_load_dwordx4 v[224:227], v10, s[98:99]
	s_add_u32 s98, s98, 0x2000
	s_addc_u32 s99, s99, 0
	global_load_dwordx4 v[228:231], v10, s[98:99] offset:-4096
	global_load_dwordx4 v[232:235], v10, s[98:99]
	s_add_u32 s98, s98, 0x2000
	s_addc_u32 s99, s99, 0
	global_load_dwordx4 v[236:239], v10, s[98:99] offset:-4096
	global_load_dwordx4 v[240:243], v10, s[98:99]
	s_add_u32 s98, s98, 0x2000
	s_addc_u32 s99, s99, 0
	global_load_dwordx4 v[244:247], v10, s[98:99] offset:-4096
	global_load_dwordx4 v[250:253], v10, s[98:99]
	s_waitcnt vmcnt(46)
	s_mov_b64 exec, -1
	v_mul_f32_e32 v192, v192, v254
	v_mul_f32_e32 v193, v193, v255
	s_mov_b64 exec, s[66:67]
	s_nop 1
	v_readlane_b32 s52, v192, 0
	v_readlane_b32 s54, v192, 1
	v_readlane_b32 s56, v192, 2
	v_readlane_b32 s58, v192, 3
	s_waitcnt vmcnt(44)
	v_pk_fma_f32 v[8:9], v[14:15], s[52:53], v[8:9] op_sel_hi:[1,0,1]
	v_pk_fma_f32 v[2:3], v[16:17], s[52:53], v[2:3] op_sel_hi:[1,0,1]
	v_pk_fma_f32 v[8:9], v[18:19], s[54:55], v[8:9] op_sel_hi:[1,0,1]
	v_pk_fma_f32 v[2:3], v[20:21], s[54:55], v[2:3] op_sel_hi:[1,0,1]
	s_add_u32 s98, s98, 0x2000
	s_addc_u32 s99, s99, 0
	global_load_dwordx4 v[14:17], v10, s[98:99] offset:-4096
	global_load_dwordx4 v[18:21], v10, s[98:99]
	v_readlane_b32 s52, v192, 4
	v_readlane_b32 s54, v192, 5
	s_waitcnt vmcnt(44)
	v_pk_fma_f32 v[8:9], v[22:23], s[56:57], v[8:9] op_sel_hi:[1,0,1]
	v_pk_fma_f32 v[2:3], v[24:25], s[56:57], v[2:3] op_sel_hi:[1,0,1]
	v_pk_fma_f32 v[8:9], v[26:27], s[58:59], v[8:9] op_sel_hi:[1,0,1]
	v_pk_fma_f32 v[2:3], v[28:29], s[58:59], v[2:3] op_sel_hi:[1,0,1]
	s_add_u32 s98, s98, 0x2000
	s_addc_u32 s99, s99, 0
	global_load_dwordx4 v[22:25], v10, s[98:99] offset:-4096
	global_load_dwordx4 v[26:29], v10, s[98:99]
	v_readlane_b32 s56, v192, 6
	v_readlane_b32 s58, v192, 7
	s_waitcnt vmcnt(44)
	v_pk_fma_f32 v[8:9], v[30:31], s[52:53], v[8:9] op_sel_hi:[1,0,1]
	v_pk_fma_f32 v[2:3], v[32:33], s[52:53], v[2:3] op_sel_hi:[1,0,1]
	v_pk_fma_f32 v[8:9], v[34:35], s[54:55], v[8:9] op_sel_hi:[1,0,1]
	v_pk_fma_f32 v[2:3], v[36:37], s[54:55], v[2:3] op_sel_hi:[1,0,1]
	s_add_u32 s98, s98, 0x2000
	s_addc_u32 s99, s99, 0
	global_load_dwordx4 v[30:33], v10, s[98:99] offset:-4096
	global_load_dwordx4 v[34:37], v10, s[98:99]
	v_readlane_b32 s52, v192, 8
	v_readlane_b32 s54, v192, 9
	s_waitcnt vmcnt(44)
	v_pk_fma_f32 v[8:9], v[38:39], s[56:57], v[8:9] op_sel_hi:[1,0,1]
	v_pk_fma_f32 v[2:3], v[40:41], s[56:57], v[2:3] op_sel_hi:[1,0,1]
	v_pk_fma_f32 v[8:9], v[42:43], s[58:59], v[8:9] op_sel_hi:[1,0,1]
	v_pk_fma_f32 v[2:3], v[44:45], s[58:59], v[2:3] op_sel_hi:[1,0,1]
	s_add_u32 s98, s98, 0x2000
	s_addc_u32 s99, s99, 0
	global_load_dwordx4 v[38:41], v10, s[98:99] offset:-4096
	global_load_dwordx4 v[42:45], v10, s[98:99]
	v_readlane_b32 s56, v192, 10
	v_readlane_b32 s58, v192, 11
	s_waitcnt vmcnt(44)
	v_pk_fma_f32 v[8:9], v[46:47], s[52:53], v[8:9] op_sel_hi:[1,0,1]
	v_pk_fma_f32 v[2:3], v[48:49], s[52:53], v[2:3] op_sel_hi:[1,0,1]
	v_pk_fma_f32 v[8:9], v[50:51], s[54:55], v[8:9] op_sel_hi:[1,0,1]
	v_pk_fma_f32 v[2:3], v[52:53], s[54:55], v[2:3] op_sel_hi:[1,0,1]
	s_add_u32 s98, s98, 0x2000
	s_addc_u32 s99, s99, 0
	global_load_dwordx4 v[46:49], v10, s[98:99] offset:-4096
	global_load_dwordx4 v[50:53], v10, s[98:99]
	v_readlane_b32 s52, v192, 12
	v_readlane_b32 s54, v192, 13
	s_waitcnt vmcnt(44)
	v_pk_fma_f32 v[8:9], v[54:55], s[56:57], v[8:9] op_sel_hi:[1,0,1]
	v_pk_fma_f32 v[2:3], v[56:57], s[56:57], v[2:3] op_sel_hi:[1,0,1]
	v_pk_fma_f32 v[8:9], v[58:59], s[58:59], v[8:9] op_sel_hi:[1,0,1]
	v_pk_fma_f32 v[2:3], v[60:61], s[58:59], v[2:3] op_sel_hi:[1,0,1]
	s_add_u32 s98, s98, 0x2000
	s_addc_u32 s99, s99, 0
	global_load_dwordx4 v[54:57], v10, s[98:99] offset:-4096
	global_load_dwordx4 v[58:61], v10, s[98:99]
	v_readlane_b32 s56, v192, 14
	v_readlane_b32 s58, v192, 15
	s_waitcnt vmcnt(44)
	v_pk_fma_f32 v[8:9], v[62:63], s[52:53], v[8:9] op_sel_hi:[1,0,1]
	v_pk_fma_f32 v[2:3], v[64:65], s[52:53], v[2:3] op_sel_hi:[1,0,1]
	v_pk_fma_f32 v[8:9], v[112:113], s[54:55], v[8:9] op_sel_hi:[1,0,1]
	v_pk_fma_f32 v[2:3], v[114:115], s[54:55], v[2:3] op_sel_hi:[1,0,1]
	s_add_u32 s98, s98, 0x2000
	s_addc_u32 s99, s99, 0
	global_load_dwordx4 v[62:65], v10, s[98:99] offset:-4096
	global_load_dwordx4 v[112:115], v10, s[98:99]
	v_readlane_b32 s52, v192, 16
	v_readlane_b32 s54, v192, 17
	s_waitcnt vmcnt(44)
	v_pk_fma_f32 v[8:9], v[116:117], s[56:57], v[8:9] op_sel_hi:[1,0,1]
	v_pk_fma_f32 v[2:3], v[118:119], s[56:57], v[2:3] op_sel_hi:[1,0,1]
	v_pk_fma_f32 v[8:9], v[120:121], s[58:59], v[8:9] op_sel_hi:[1,0,1]
	v_pk_fma_f32 v[2:3], v[122:123], s[58:59], v[2:3] op_sel_hi:[1,0,1]
	s_add_u32 s98, s98, 0x2000
	s_addc_u32 s99, s99, 0
	global_load_dwordx4 v[116:119], v10, s[98:99] offset:-4096
	global_load_dwordx4 v[120:123], v10, s[98:99]
	v_readlane_b32 s56, v192, 18
	v_readlane_b32 s58, v192, 19
	s_waitcnt vmcnt(44)
	v_pk_fma_f32 v[8:9], v[124:125], s[52:53], v[8:9] op_sel_hi:[1,0,1]
	v_pk_fma_f32 v[2:3], v[126:127], s[52:53], v[2:3] op_sel_hi:[1,0,1]
	v_pk_fma_f32 v[8:9], v[128:129], s[54:55], v[8:9] op_sel_hi:[1,0,1]
	v_pk_fma_f32 v[2:3], v[130:131], s[54:55], v[2:3] op_sel_hi:[1,0,1]
	s_add_u32 s98, s98, 0x2000
	s_addc_u32 s99, s99, 0
	global_load_dwordx4 v[124:127], v10, s[98:99] offset:-4096
	global_load_dwordx4 v[128:131], v10, s[98:99]
	v_readlane_b32 s52, v192, 20
	v_readlane_b32 s54, v192, 21
	s_waitcnt vmcnt(44)
	v_pk_fma_f32 v[8:9], v[132:133], s[56:57], v[8:9] op_sel_hi:[1,0,1]
	v_pk_fma_f32 v[2:3], v[134:135], s[56:57], v[2:3] op_sel_hi:[1,0,1]
	v_pk_fma_f32 v[8:9], v[136:137], s[58:59], v[8:9] op_sel_hi:[1,0,1]
	v_pk_fma_f32 v[2:3], v[138:139], s[58:59], v[2:3] op_sel_hi:[1,0,1]
	s_add_u32 s98, s98, 0x2000
	s_addc_u32 s99, s99, 0
	global_load_dwordx4 v[132:135], v10, s[98:99] offset:-4096
	global_load_dwordx4 v[136:139], v10, s[98:99]
	v_readlane_b32 s56, v192, 22
	v_readlane_b32 s58, v192, 23
	s_waitcnt vmcnt(44)
	v_pk_fma_f32 v[8:9], v[140:141], s[52:53], v[8:9] op_sel_hi:[1,0,1]
	v_pk_fma_f32 v[2:3], v[142:143], s[52:53], v[2:3] op_sel_hi:[1,0,1]
	v_pk_fma_f32 v[8:9], v[144:145], s[54:55], v[8:9] op_sel_hi:[1,0,1]
	v_pk_fma_f32 v[2:3], v[146:147], s[54:55], v[2:3] op_sel_hi:[1,0,1]
	s_add_u32 s98, s98, 0x2000
	s_addc_u32 s99, s99, 0
	global_load_dwordx4 v[140:143], v10, s[98:99] offset:-4096
	global_load_dwordx4 v[144:147], v10, s[98:99]
	v_readlane_b32 s52, v192, 24
	v_readlane_b32 s54, v192, 25
	s_waitcnt vmcnt(44)
	v_pk_fma_f32 v[8:9], v[148:149], s[56:57], v[8:9] op_sel_hi:[1,0,1]
	v_pk_fma_f32 v[2:3], v[150:151], s[56:57], v[2:3] op_sel_hi:[1,0,1]
	v_pk_fma_f32 v[8:9], v[152:153], s[58:59], v[8:9] op_sel_hi:[1,0,1]
	v_pk_fma_f32 v[2:3], v[154:155], s[58:59], v[2:3] op_sel_hi:[1,0,1]
	s_add_u32 s98, s98, 0x2000
	s_addc_u32 s99, s99, 0
	global_load_dwordx4 v[148:151], v10, s[98:99] offset:-4096
	global_load_dwordx4 v[152:155], v10, s[98:99]
	v_readlane_b32 s56, v192, 26
	v_readlane_b32 s58, v192, 27
	s_waitcnt vmcnt(44)
	v_pk_fma_f32 v[8:9], v[156:157], s[52:53], v[8:9] op_sel_hi:[1,0,1]
	v_pk_fma_f32 v[2:3], v[158:159], s[52:53], v[2:3] op_sel_hi:[1,0,1]
	v_pk_fma_f32 v[8:9], v[160:161], s[54:55], v[8:9] op_sel_hi:[1,0,1]
	v_pk_fma_f32 v[2:3], v[162:163], s[54:55], v[2:3] op_sel_hi:[1,0,1]
	s_add_u32 s98, s98, 0x2000
	s_addc_u32 s99, s99, 0
	global_load_dwordx4 v[156:159], v10, s[98:99] offset:-4096
	global_load_dwordx4 v[160:163], v10, s[98:99]
	v_readlane_b32 s52, v192, 28
	v_readlane_b32 s54, v192, 29
	s_waitcnt vmcnt(44)
	v_pk_fma_f32 v[8:9], v[164:165], s[56:57], v[8:9] op_sel_hi:[1,0,1]
	v_pk_fma_f32 v[2:3], v[166:167], s[56:57], v[2:3] op_sel_hi:[1,0,1]
	v_pk_fma_f32 v[8:9], v[168:169], s[58:59], v[8:9] op_sel_hi:[1,0,1]
	v_pk_fma_f32 v[2:3], v[170:171], s[58:59], v[2:3] op_sel_hi:[1,0,1]
	s_add_u32 s98, s98, 0x2000
	s_addc_u32 s99, s99, 0
	global_load_dwordx4 v[164:167], v10, s[98:99] offset:-4096
	global_load_dwordx4 v[168:171], v10, s[98:99]
	v_readlane_b32 s56, v192, 30
	v_readlane_b32 s58, v192, 31
	s_waitcnt vmcnt(44)
	v_pk_fma_f32 v[8:9], v[172:173], s[52:53], v[8:9] op_sel_hi:[1,0,1]
	v_pk_fma_f32 v[2:3], v[174:175], s[52:53], v[2:3] op_sel_hi:[1,0,1]
	v_pk_fma_f32 v[8:9], v[176:177], s[54:55], v[8:9] op_sel_hi:[1,0,1]
	v_pk_fma_f32 v[2:3], v[178:179], s[54:55], v[2:3] op_sel_hi:[1,0,1]
	s_add_u32 s98, s98, 0x2000
	s_addc_u32 s99, s99, 0
	global_load_dwordx4 v[172:175], v10, s[98:99] offset:-4096
	global_load_dwordx4 v[176:179], v10, s[98:99]
	v_readlane_b32 s52, v192, 32
	v_readlane_b32 s54, v192, 33
	s_waitcnt vmcnt(44)
	v_pk_fma_f32 v[8:9], v[180:181], s[56:57], v[8:9] op_sel_hi:[1,0,1]
	v_pk_fma_f32 v[2:3], v[182:183], s[56:57], v[2:3] op_sel_hi:[1,0,1]
	v_pk_fma_f32 v[8:9], v[184:185], s[58:59], v[8:9] op_sel_hi:[1,0,1]
	v_pk_fma_f32 v[2:3], v[186:187], s[58:59], v[2:3] op_sel_hi:[1,0,1]
	s_add_u32 s98, s98, 0x2000
	s_addc_u32 s99, s99, 0
	global_load_dwordx4 v[180:183], v10, s[98:99] offset:-4096
	global_load_dwordx4 v[184:187], v10, s[98:99]
	v_readlane_b32 s56, v192, 34
	v_readlane_b32 s58, v192, 35
	s_waitcnt vmcnt(44)
	v_pk_fma_f32 v[8:9], v[188:189], s[52:53], v[8:9] op_sel_hi:[1,0,1]
	v_pk_fma_f32 v[2:3], v[190:191], s[52:53], v[2:3] op_sel_hi:[1,0,1]
	v_pk_fma_f32 v[8:9], v[198:199], s[54:55], v[8:9] op_sel_hi:[1,0,1]
	v_pk_fma_f32 v[2:3], v[200:201], s[54:55], v[2:3] op_sel_hi:[1,0,1]
	s_add_u32 s98, s98, 0x2000
	s_addc_u32 s99, s99, 0
	global_load_dwordx4 v[188:191], v10, s[98:99] offset:-4096
	global_load_dwordx4 v[198:201], v10, s[98:99]
	v_readlane_b32 s52, v192, 36
	v_readlane_b32 s54, v192, 37
	s_waitcnt vmcnt(44)
	v_pk_fma_f32 v[8:9], v[202:203], s[56:57], v[8:9] op_sel_hi:[1,0,1]
	v_pk_fma_f32 v[2:3], v[204:205], s[56:57], v[2:3] op_sel_hi:[1,0,1]
	v_pk_fma_f32 v[8:9], v[206:207], s[58:59], v[8:9] op_sel_hi:[1,0,1]
	v_pk_fma_f32 v[2:3], v[208:209], s[58:59], v[2:3] op_sel_hi:[1,0,1]
	s_add_u32 s98, s98, 0x2000
	s_addc_u32 s99, s99, 0
	global_load_dwordx4 v[202:205], v10, s[98:99] offset:-4096
	global_load_dwordx4 v[206:209], v10, s[98:99]
	v_readlane_b32 s56, v192, 38
	v_readlane_b32 s58, v192, 39
	s_waitcnt vmcnt(44)
	v_pk_fma_f32 v[8:9], v[212:213], s[52:53], v[8:9] op_sel_hi:[1,0,1]
	v_pk_fma_f32 v[2:3], v[214:215], s[52:53], v[2:3] op_sel_hi:[1,0,1]
	v_pk_fma_f32 v[8:9], v[216:217], s[54:55], v[8:9] op_sel_hi:[1,0,1]
	v_pk_fma_f32 v[2:3], v[218:219], s[54:55], v[2:3] op_sel_hi:[1,0,1]
	s_add_u32 s98, s98, 0x2000
	s_addc_u32 s99, s99, 0
	global_load_dwordx4 v[212:215], v10, s[98:99] offset:-4096
	global_load_dwordx4 v[216:219], v10, s[98:99]
	v_readlane_b32 s52, v192, 40
	v_readlane_b32 s54, v192, 41
	s_waitcnt vmcnt(44)
	v_pk_fma_f32 v[8:9], v[220:221], s[56:57], v[8:9] op_sel_hi:[1,0,1]
	v_pk_fma_f32 v[2:3], v[222:223], s[56:57], v[2:3] op_sel_hi:[1,0,1]
	v_pk_fma_f32 v[8:9], v[224:225], s[58:59], v[8:9] op_sel_hi:[1,0,1]
	v_pk_fma_f32 v[2:3], v[226:227], s[58:59], v[2:3] op_sel_hi:[1,0,1]
	s_add_u32 s98, s98, 0x2000
	s_addc_u32 s99, s99, 0
	global_load_dwordx4 v[220:223], v10, s[98:99] offset:-4096
	global_load_dwordx4 v[224:227], v10, s[98:99]
	v_readlane_b32 s56, v192, 42
	v_readlane_b32 s58, v192, 43
	s_waitcnt vmcnt(44)
	v_pk_fma_f32 v[8:9], v[228:229], s[52:53], v[8:9] op_sel_hi:[1,0,1]
	v_pk_fma_f32 v[2:3], v[230:231], s[52:53], v[2:3] op_sel_hi:[1,0,1]
	v_pk_fma_f32 v[8:9], v[232:233], s[54:55], v[8:9] op_sel_hi:[1,0,1]
	v_pk_fma_f32 v[2:3], v[234:235], s[54:55], v[2:3] op_sel_hi:[1,0,1]
	s_add_u32 s98, s98, 0x2000
	s_addc_u32 s99, s99, 0
	global_load_dwordx4 v[228:231], v10, s[98:99] offset:-4096
	global_load_dwordx4 v[232:235], v10, s[98:99]
	v_readlane_b32 s52, v192, 44
	v_readlane_b32 s54, v192, 45
	s_waitcnt vmcnt(44)
	v_pk_fma_f32 v[8:9], v[236:237], s[56:57], v[8:9] op_sel_hi:[1,0,1]
	v_pk_fma_f32 v[2:3], v[238:239], s[56:57], v[2:3] op_sel_hi:[1,0,1]
	v_pk_fma_f32 v[8:9], v[240:241], s[58:59], v[8:9] op_sel_hi:[1,0,1]
	v_pk_fma_f32 v[2:3], v[242:243], s[58:59], v[2:3] op_sel_hi:[1,0,1]
	s_add_u32 s98, s98, 0x2000
	s_addc_u32 s99, s99, 0
	global_load_dwordx4 v[236:239], v10, s[98:99] offset:-4096
	global_load_dwordx4 v[240:243], v10, s[98:99]
	v_readlane_b32 s56, v192, 46
	v_readlane_b32 s58, v192, 47
	s_waitcnt vmcnt(44)
	v_pk_fma_f32 v[8:9], v[244:245], s[52:53], v[8:9] op_sel_hi:[1,0,1]
	v_pk_fma_f32 v[2:3], v[246:247], s[52:53], v[2:3] op_sel_hi:[1,0,1]
	v_pk_fma_f32 v[8:9], v[250:251], s[54:55], v[8:9] op_sel_hi:[1,0,1]
	v_pk_fma_f32 v[2:3], v[252:253], s[54:55], v[2:3] op_sel_hi:[1,0,1]
	s_add_u32 s98, s98, 0x2000
	s_addc_u32 s99, s99, 0
	global_load_dwordx4 v[244:247], v10, s[98:99] offset:-4096
	global_load_dwordx4 v[250:253], v10, s[98:99]
	v_readlane_b32 s52, v192, 48
	v_readlane_b32 s54, v192, 49
	s_waitcnt vmcnt(44)
	v_pk_fma_f32 v[8:9], v[14:15], s[56:57], v[8:9] op_sel_hi:[1,0,1]
	v_pk_fma_f32 v[2:3], v[16:17], s[56:57], v[2:3] op_sel_hi:[1,0,1]
	v_pk_fma_f32 v[8:9], v[18:19], s[58:59], v[8:9] op_sel_hi:[1,0,1]
	v_pk_fma_f32 v[2:3], v[20:21], s[58:59], v[2:3] op_sel_hi:[1,0,1]
	s_add_u32 s98, s98, 0x2000
	s_addc_u32 s99, s99, 0
	global_load_dwordx4 v[14:17], v10, s[98:99] offset:-4096
	global_load_dwordx4 v[18:21], v10, s[98:99]
	v_readlane_b32 s56, v192, 50
	v_readlane_b32 s58, v192, 51
	s_waitcnt vmcnt(44)
	v_pk_fma_f32 v[8:9], v[22:23], s[52:53], v[8:9] op_sel_hi:[1,0,1]
	v_pk_fma_f32 v[2:3], v[24:25], s[52:53], v[2:3] op_sel_hi:[1,0,1]
	v_pk_fma_f32 v[8:9], v[26:27], s[54:55], v[8:9] op_sel_hi:[1,0,1]
	v_pk_fma_f32 v[2:3], v[28:29], s[54:55], v[2:3] op_sel_hi:[1,0,1]
	s_add_u32 s98, s98, 0x2000
	s_addc_u32 s99, s99, 0
	global_load_dwordx4 v[22:25], v10, s[98:99] offset:-4096
	global_load_dwordx4 v[26:29], v10, s[98:99]
	v_readlane_b32 s52, v192, 52
	v_readlane_b32 s54, v192, 53
	s_waitcnt vmcnt(44)
	v_pk_fma_f32 v[8:9], v[30:31], s[56:57], v[8:9] op_sel_hi:[1,0,1]
	v_pk_fma_f32 v[2:3], v[32:33], s[56:57], v[2:3] op_sel_hi:[1,0,1]
	v_pk_fma_f32 v[8:9], v[34:35], s[58:59], v[8:9] op_sel_hi:[1,0,1]
	v_pk_fma_f32 v[2:3], v[36:37], s[58:59], v[2:3] op_sel_hi:[1,0,1]
	s_add_u32 s98, s98, 0x2000
	s_addc_u32 s99, s99, 0
	global_load_dwordx4 v[30:33], v10, s[98:99] offset:-4096
	global_load_dwordx4 v[34:37], v10, s[98:99]
	v_readlane_b32 s56, v192, 54
	v_readlane_b32 s58, v192, 55
	s_waitcnt vmcnt(44)
	v_pk_fma_f32 v[8:9], v[38:39], s[52:53], v[8:9] op_sel_hi:[1,0,1]
	v_pk_fma_f32 v[2:3], v[40:41], s[52:53], v[2:3] op_sel_hi:[1,0,1]
	v_pk_fma_f32 v[8:9], v[42:43], s[54:55], v[8:9] op_sel_hi:[1,0,1]
	v_pk_fma_f32 v[2:3], v[44:45], s[54:55], v[2:3] op_sel_hi:[1,0,1]
	s_add_u32 s98, s98, 0x2000
	s_addc_u32 s99, s99, 0
	global_load_dwordx4 v[38:41], v10, s[98:99] offset:-4096
	global_load_dwordx4 v[42:45], v10, s[98:99]
	v_readlane_b32 s52, v192, 56
	v_readlane_b32 s54, v192, 57
	s_waitcnt vmcnt(44)
	v_pk_fma_f32 v[8:9], v[46:47], s[56:57], v[8:9] op_sel_hi:[1,0,1]
	v_pk_fma_f32 v[2:3], v[48:49], s[56:57], v[2:3] op_sel_hi:[1,0,1]
	v_pk_fma_f32 v[8:9], v[50:51], s[58:59], v[8:9] op_sel_hi:[1,0,1]
	v_pk_fma_f32 v[2:3], v[52:53], s[58:59], v[2:3] op_sel_hi:[1,0,1]
	s_add_u32 s98, s98, 0x2000
	s_addc_u32 s99, s99, 0
	global_load_dwordx4 v[46:49], v10, s[98:99] offset:-4096
	global_load_dwordx4 v[50:53], v10, s[98:99]
	v_readlane_b32 s56, v192, 58
	v_readlane_b32 s58, v192, 59
	s_waitcnt vmcnt(44)
	v_pk_fma_f32 v[8:9], v[54:55], s[52:53], v[8:9] op_sel_hi:[1,0,1]
	v_pk_fma_f32 v[2:3], v[56:57], s[52:53], v[2:3] op_sel_hi:[1,0,1]
	v_pk_fma_f32 v[8:9], v[58:59], s[54:55], v[8:9] op_sel_hi:[1,0,1]
	v_pk_fma_f32 v[2:3], v[60:61], s[54:55], v[2:3] op_sel_hi:[1,0,1]
	s_add_u32 s98, s98, 0x2000
	s_addc_u32 s99, s99, 0
	global_load_dwordx4 v[54:57], v10, s[98:99] offset:-4096
	global_load_dwordx4 v[58:61], v10, s[98:99]
	v_readlane_b32 s52, v192, 60
	v_readlane_b32 s54, v192, 61
	s_waitcnt vmcnt(44)
	v_pk_fma_f32 v[8:9], v[62:63], s[56:57], v[8:9] op_sel_hi:[1,0,1]
	v_pk_fma_f32 v[2:3], v[64:65], s[56:57], v[2:3] op_sel_hi:[1,0,1]
	v_pk_fma_f32 v[8:9], v[112:113], s[58:59], v[8:9] op_sel_hi:[1,0,1]
	v_pk_fma_f32 v[2:3], v[114:115], s[58:59], v[2:3] op_sel_hi:[1,0,1]
	s_add_u32 s98, s98, 0x2000
	s_addc_u32 s99, s99, 0
	global_load_dwordx4 v[62:65], v10, s[98:99] offset:-4096
	global_load_dwordx4 v[112:115], v10, s[98:99]
	v_readlane_b32 s56, v192, 62
	v_readlane_b32 s58, v192, 63
	s_waitcnt vmcnt(44)
	v_pk_fma_f32 v[8:9], v[116:117], s[52:53], v[8:9] op_sel_hi:[1,0,1]
	v_pk_fma_f32 v[2:3], v[118:119], s[52:53], v[2:3] op_sel_hi:[1,0,1]
	v_pk_fma_f32 v[8:9], v[120:121], s[54:55], v[8:9] op_sel_hi:[1,0,1]
	v_pk_fma_f32 v[2:3], v[122:123], s[54:55], v[2:3] op_sel_hi:[1,0,1]
	s_add_u32 s98, s98, 0x2000
	s_addc_u32 s99, s99, 0
	global_load_dwordx4 v[116:119], v10, s[98:99] offset:-4096
	global_load_dwordx4 v[120:123], v10, s[98:99]
	v_readlane_b32 s52, v193, 0
	v_readlane_b32 s54, v193, 1
	s_waitcnt vmcnt(44)
	v_pk_fma_f32 v[8:9], v[124:125], s[56:57], v[8:9] op_sel_hi:[1,0,1]
	v_pk_fma_f32 v[2:3], v[126:127], s[56:57], v[2:3] op_sel_hi:[1,0,1]
	v_pk_fma_f32 v[8:9], v[128:129], s[58:59], v[8:9] op_sel_hi:[1,0,1]
	v_pk_fma_f32 v[2:3], v[130:131], s[58:59], v[2:3] op_sel_hi:[1,0,1]
	s_add_u32 s98, s98, 0x2000
	s_addc_u32 s99, s99, 0
	global_load_dwordx4 v[124:127], v10, s[98:99] offset:-4096
	global_load_dwordx4 v[128:131], v10, s[98:99]
	v_readlane_b32 s56, v193, 2
	v_readlane_b32 s58, v193, 3
	s_waitcnt vmcnt(44)
	v_pk_fma_f32 v[8:9], v[132:133], s[52:53], v[8:9] op_sel_hi:[1,0,1]
	v_pk_fma_f32 v[2:3], v[134:135], s[52:53], v[2:3] op_sel_hi:[1,0,1]
	v_pk_fma_f32 v[8:9], v[136:137], s[54:55], v[8:9] op_sel_hi:[1,0,1]
	v_pk_fma_f32 v[2:3], v[138:139], s[54:55], v[2:3] op_sel_hi:[1,0,1]
	s_add_u32 s98, s98, 0x2000
	s_addc_u32 s99, s99, 0
	global_load_dwordx4 v[132:135], v10, s[98:99] offset:-4096
	global_load_dwordx4 v[136:139], v10, s[98:99]
	v_readlane_b32 s52, v193, 4
	v_readlane_b32 s54, v193, 5
	s_waitcnt vmcnt(44)
	v_pk_fma_f32 v[8:9], v[140:141], s[56:57], v[8:9] op_sel_hi:[1,0,1]
	v_pk_fma_f32 v[2:3], v[142:143], s[56:57], v[2:3] op_sel_hi:[1,0,1]
	v_pk_fma_f32 v[8:9], v[144:145], s[58:59], v[8:9] op_sel_hi:[1,0,1]
	v_pk_fma_f32 v[2:3], v[146:147], s[58:59], v[2:3] op_sel_hi:[1,0,1]
	s_add_u32 s98, s98, 0x2000
	s_addc_u32 s99, s99, 0
	global_load_dwordx4 v[140:143], v10, s[98:99] offset:-4096
	global_load_dwordx4 v[144:147], v10, s[98:99]
	v_readlane_b32 s56, v193, 6
	v_readlane_b32 s58, v193, 7
	s_waitcnt vmcnt(44)
	v_pk_fma_f32 v[8:9], v[148:149], s[52:53], v[8:9] op_sel_hi:[1,0,1]
	v_pk_fma_f32 v[2:3], v[150:151], s[52:53], v[2:3] op_sel_hi:[1,0,1]
	v_pk_fma_f32 v[8:9], v[152:153], s[54:55], v[8:9] op_sel_hi:[1,0,1]
	v_pk_fma_f32 v[2:3], v[154:155], s[54:55], v[2:3] op_sel_hi:[1,0,1]
	s_add_u32 s98, s98, 0x2000
	s_addc_u32 s99, s99, 0
	global_load_dwordx4 v[148:151], v10, s[98:99] offset:-4096
	global_load_dwordx4 v[152:155], v10, s[98:99]
	v_readlane_b32 s52, v193, 8
	v_readlane_b32 s54, v193, 9
	s_waitcnt vmcnt(44)
	v_pk_fma_f32 v[8:9], v[156:157], s[56:57], v[8:9] op_sel_hi:[1,0,1]
	v_pk_fma_f32 v[2:3], v[158:159], s[56:57], v[2:3] op_sel_hi:[1,0,1]
	v_pk_fma_f32 v[8:9], v[160:161], s[58:59], v[8:9] op_sel_hi:[1,0,1]
	v_pk_fma_f32 v[2:3], v[162:163], s[58:59], v[2:3] op_sel_hi:[1,0,1]
	s_add_u32 s98, s98, 0x2000
	s_addc_u32 s99, s99, 0
	global_load_dwordx4 v[156:159], v10, s[98:99] offset:-4096
	global_load_dwordx4 v[160:163], v10, s[98:99]
	v_readlane_b32 s56, v193, 10
	v_readlane_b32 s58, v193, 11
	s_waitcnt vmcnt(44)
	v_pk_fma_f32 v[8:9], v[164:165], s[52:53], v[8:9] op_sel_hi:[1,0,1]
	v_pk_fma_f32 v[2:3], v[166:167], s[52:53], v[2:3] op_sel_hi:[1,0,1]
	v_pk_fma_f32 v[8:9], v[168:169], s[54:55], v[8:9] op_sel_hi:[1,0,1]
	v_pk_fma_f32 v[2:3], v[170:171], s[54:55], v[2:3] op_sel_hi:[1,0,1]
	s_add_u32 s98, s98, 0x2000
	s_addc_u32 s99, s99, 0
	global_load_dwordx4 v[164:167], v10, s[98:99] offset:-4096
	global_load_dwordx4 v[168:171], v10, s[98:99]
	v_readlane_b32 s52, v193, 12
	v_readlane_b32 s54, v193, 13
	s_waitcnt vmcnt(44)
	v_pk_fma_f32 v[8:9], v[172:173], s[56:57], v[8:9] op_sel_hi:[1,0,1]
	v_pk_fma_f32 v[2:3], v[174:175], s[56:57], v[2:3] op_sel_hi:[1,0,1]
	v_pk_fma_f32 v[8:9], v[176:177], s[58:59], v[8:9] op_sel_hi:[1,0,1]
	v_pk_fma_f32 v[2:3], v[178:179], s[58:59], v[2:3] op_sel_hi:[1,0,1]
	s_add_u32 s98, s98, 0x2000
	s_addc_u32 s99, s99, 0
	global_load_dwordx4 v[172:175], v10, s[98:99] offset:-4096
	global_load_dwordx4 v[176:179], v10, s[98:99]
	v_readlane_b32 s56, v193, 14
	v_readlane_b32 s58, v193, 15
	s_waitcnt vmcnt(44)
	v_pk_fma_f32 v[8:9], v[180:181], s[52:53], v[8:9] op_sel_hi:[1,0,1]
	v_pk_fma_f32 v[2:3], v[182:183], s[52:53], v[2:3] op_sel_hi:[1,0,1]
	v_pk_fma_f32 v[8:9], v[184:185], s[54:55], v[8:9] op_sel_hi:[1,0,1]
	v_pk_fma_f32 v[2:3], v[186:187], s[54:55], v[2:3] op_sel_hi:[1,0,1]
	s_add_u32 s98, s98, 0x2000
	s_addc_u32 s99, s99, 0
	global_load_dwordx4 v[180:183], v10, s[98:99] offset:-4096
	global_load_dwordx4 v[184:187], v10, s[98:99]
	v_readlane_b32 s52, v193, 16
	v_readlane_b32 s54, v193, 17
	s_waitcnt vmcnt(44)
	v_pk_fma_f32 v[8:9], v[188:189], s[56:57], v[8:9] op_sel_hi:[1,0,1]
	v_pk_fma_f32 v[2:3], v[190:191], s[56:57], v[2:3] op_sel_hi:[1,0,1]
	v_pk_fma_f32 v[8:9], v[198:199], s[58:59], v[8:9] op_sel_hi:[1,0,1]
	v_pk_fma_f32 v[2:3], v[200:201], s[58:59], v[2:3] op_sel_hi:[1,0,1]
	s_add_u32 s98, s98, 0x2000
	s_addc_u32 s99, s99, 0
	global_load_dwordx4 v[188:191], v10, s[98:99] offset:-4096
	global_load_dwordx4 v[198:201], v10, s[98:99]
	v_readlane_b32 s56, v193, 18
	v_readlane_b32 s58, v193, 19
	s_waitcnt vmcnt(44)
	v_pk_fma_f32 v[8:9], v[202:203], s[52:53], v[8:9] op_sel_hi:[1,0,1]
	v_pk_fma_f32 v[2:3], v[204:205], s[52:53], v[2:3] op_sel_hi:[1,0,1]
	v_pk_fma_f32 v[8:9], v[206:207], s[54:55], v[8:9] op_sel_hi:[1,0,1]
	v_pk_fma_f32 v[2:3], v[208:209], s[54:55], v[2:3] op_sel_hi:[1,0,1]
	s_add_u32 s98, s98, 0x2000
	s_addc_u32 s99, s99, 0
	global_load_dwordx4 v[202:205], v10, s[98:99] offset:-4096
	global_load_dwordx4 v[206:209], v10, s[98:99]
	v_readlane_b32 s52, v193, 20
	v_readlane_b32 s54, v193, 21
	s_waitcnt vmcnt(44)
	v_pk_fma_f32 v[8:9], v[212:213], s[56:57], v[8:9] op_sel_hi:[1,0,1]
	v_pk_fma_f32 v[2:3], v[214:215], s[56:57], v[2:3] op_sel_hi:[1,0,1]
	v_pk_fma_f32 v[8:9], v[216:217], s[58:59], v[8:9] op_sel_hi:[1,0,1]
	v_pk_fma_f32 v[2:3], v[218:219], s[58:59], v[2:3] op_sel_hi:[1,0,1]
	v_readlane_b32 s56, v193, 22
	v_readlane_b32 s58, v193, 23
	s_waitcnt vmcnt(42)
	v_pk_fma_f32 v[8:9], v[220:221], s[52:53], v[8:9] op_sel_hi:[1,0,1]
	v_pk_fma_f32 v[2:3], v[222:223], s[52:53], v[2:3] op_sel_hi:[1,0,1]
	v_pk_fma_f32 v[8:9], v[224:225], s[54:55], v[8:9] op_sel_hi:[1,0,1]
	v_pk_fma_f32 v[2:3], v[226:227], s[54:55], v[2:3] op_sel_hi:[1,0,1]
	v_readlane_b32 s52, v193, 24
	v_readlane_b32 s54, v193, 25
	s_waitcnt vmcnt(40)
	v_pk_fma_f32 v[8:9], v[228:229], s[56:57], v[8:9] op_sel_hi:[1,0,1]
	v_pk_fma_f32 v[2:3], v[230:231], s[56:57], v[2:3] op_sel_hi:[1,0,1]
	v_pk_fma_f32 v[8:9], v[232:233], s[58:59], v[8:9] op_sel_hi:[1,0,1]
	v_pk_fma_f32 v[2:3], v[234:235], s[58:59], v[2:3] op_sel_hi:[1,0,1]
	v_readlane_b32 s56, v193, 26
	v_readlane_b32 s58, v193, 27
	s_waitcnt vmcnt(38)
	v_pk_fma_f32 v[8:9], v[236:237], s[52:53], v[8:9] op_sel_hi:[1,0,1]
	v_pk_fma_f32 v[2:3], v[238:239], s[52:53], v[2:3] op_sel_hi:[1,0,1]
	v_pk_fma_f32 v[8:9], v[240:241], s[54:55], v[8:9] op_sel_hi:[1,0,1]
	v_pk_fma_f32 v[2:3], v[242:243], s[54:55], v[2:3] op_sel_hi:[1,0,1]
	v_readlane_b32 s52, v193, 28
	v_readlane_b32 s54, v193, 29
	s_waitcnt vmcnt(36)
	v_pk_fma_f32 v[8:9], v[244:245], s[56:57], v[8:9] op_sel_hi:[1,0,1]
	v_pk_fma_f32 v[2:3], v[246:247], s[56:57], v[2:3] op_sel_hi:[1,0,1]
	v_pk_fma_f32 v[8:9], v[250:251], s[58:59], v[8:9] op_sel_hi:[1,0,1]
	v_pk_fma_f32 v[2:3], v[252:253], s[58:59], v[2:3] op_sel_hi:[1,0,1]
	v_readlane_b32 s56, v193, 30
	v_readlane_b32 s58, v193, 31
	s_waitcnt vmcnt(34)
	v_pk_fma_f32 v[8:9], v[14:15], s[52:53], v[8:9] op_sel_hi:[1,0,1]
	v_pk_fma_f32 v[2:3], v[16:17], s[52:53], v[2:3] op_sel_hi:[1,0,1]
	v_pk_fma_f32 v[8:9], v[18:19], s[54:55], v[8:9] op_sel_hi:[1,0,1]
	v_pk_fma_f32 v[2:3], v[20:21], s[54:55], v[2:3] op_sel_hi:[1,0,1]
	v_readlane_b32 s52, v193, 32
	v_readlane_b32 s54, v193, 33
	s_waitcnt vmcnt(32)
	v_pk_fma_f32 v[8:9], v[22:23], s[56:57], v[8:9] op_sel_hi:[1,0,1]
	v_pk_fma_f32 v[2:3], v[24:25], s[56:57], v[2:3] op_sel_hi:[1,0,1]
	v_pk_fma_f32 v[8:9], v[26:27], s[58:59], v[8:9] op_sel_hi:[1,0,1]
	v_pk_fma_f32 v[2:3], v[28:29], s[58:59], v[2:3] op_sel_hi:[1,0,1]
	v_readlane_b32 s56, v193, 34
	v_readlane_b32 s58, v193, 35
	s_waitcnt vmcnt(30)
	v_pk_fma_f32 v[8:9], v[30:31], s[52:53], v[8:9] op_sel_hi:[1,0,1]
	v_pk_fma_f32 v[2:3], v[32:33], s[52:53], v[2:3] op_sel_hi:[1,0,1]
	v_pk_fma_f32 v[8:9], v[34:35], s[54:55], v[8:9] op_sel_hi:[1,0,1]
	v_pk_fma_f32 v[2:3], v[36:37], s[54:55], v[2:3] op_sel_hi:[1,0,1]
	v_readlane_b32 s52, v193, 36
	v_readlane_b32 s54, v193, 37
	s_waitcnt vmcnt(28)
	v_pk_fma_f32 v[8:9], v[38:39], s[56:57], v[8:9] op_sel_hi:[1,0,1]
	v_pk_fma_f32 v[2:3], v[40:41], s[56:57], v[2:3] op_sel_hi:[1,0,1]
	v_pk_fma_f32 v[8:9], v[42:43], s[58:59], v[8:9] op_sel_hi:[1,0,1]
	v_pk_fma_f32 v[2:3], v[44:45], s[58:59], v[2:3] op_sel_hi:[1,0,1]
	v_readlane_b32 s56, v193, 38
	v_readlane_b32 s58, v193, 39
	s_waitcnt vmcnt(26)
	v_pk_fma_f32 v[8:9], v[46:47], s[52:53], v[8:9] op_sel_hi:[1,0,1]
	v_pk_fma_f32 v[2:3], v[48:49], s[52:53], v[2:3] op_sel_hi:[1,0,1]
	v_pk_fma_f32 v[8:9], v[50:51], s[54:55], v[8:9] op_sel_hi:[1,0,1]
	v_pk_fma_f32 v[2:3], v[52:53], s[54:55], v[2:3] op_sel_hi:[1,0,1]
	v_readlane_b32 s52, v193, 40
	v_readlane_b32 s54, v193, 41
	s_waitcnt vmcnt(24)
	v_pk_fma_f32 v[8:9], v[54:55], s[56:57], v[8:9] op_sel_hi:[1,0,1]
	v_pk_fma_f32 v[2:3], v[56:57], s[56:57], v[2:3] op_sel_hi:[1,0,1]
	v_pk_fma_f32 v[8:9], v[58:59], s[58:59], v[8:9] op_sel_hi:[1,0,1]
	v_pk_fma_f32 v[2:3], v[60:61], s[58:59], v[2:3] op_sel_hi:[1,0,1]
	v_readlane_b32 s56, v193, 42
	v_readlane_b32 s58, v193, 43
	s_waitcnt vmcnt(22)
	v_pk_fma_f32 v[8:9], v[62:63], s[52:53], v[8:9] op_sel_hi:[1,0,1]
	v_pk_fma_f32 v[2:3], v[64:65], s[52:53], v[2:3] op_sel_hi:[1,0,1]
	v_pk_fma_f32 v[8:9], v[112:113], s[54:55], v[8:9] op_sel_hi:[1,0,1]
	v_pk_fma_f32 v[2:3], v[114:115], s[54:55], v[2:3] op_sel_hi:[1,0,1]
	v_readlane_b32 s52, v193, 44
	v_readlane_b32 s54, v193, 45
	s_waitcnt vmcnt(20)
	v_pk_fma_f32 v[8:9], v[116:117], s[56:57], v[8:9] op_sel_hi:[1,0,1]
	v_pk_fma_f32 v[2:3], v[118:119], s[56:57], v[2:3] op_sel_hi:[1,0,1]
	v_pk_fma_f32 v[8:9], v[120:121], s[58:59], v[8:9] op_sel_hi:[1,0,1]
	v_pk_fma_f32 v[2:3], v[122:123], s[58:59], v[2:3] op_sel_hi:[1,0,1]
	v_readlane_b32 s56, v193, 46
	v_readlane_b32 s58, v193, 47
	s_waitcnt vmcnt(18)
	v_pk_fma_f32 v[8:9], v[124:125], s[52:53], v[8:9] op_sel_hi:[1,0,1]
	v_pk_fma_f32 v[2:3], v[126:127], s[52:53], v[2:3] op_sel_hi:[1,0,1]
	v_pk_fma_f32 v[8:9], v[128:129], s[54:55], v[8:9] op_sel_hi:[1,0,1]
	v_pk_fma_f32 v[2:3], v[130:131], s[54:55], v[2:3] op_sel_hi:[1,0,1]
	v_readlane_b32 s52, v193, 48
	v_readlane_b32 s54, v193, 49
	s_waitcnt vmcnt(16)
	v_pk_fma_f32 v[8:9], v[132:133], s[56:57], v[8:9] op_sel_hi:[1,0,1]
	v_pk_fma_f32 v[2:3], v[134:135], s[56:57], v[2:3] op_sel_hi:[1,0,1]
	v_pk_fma_f32 v[8:9], v[136:137], s[58:59], v[8:9] op_sel_hi:[1,0,1]
	v_pk_fma_f32 v[2:3], v[138:139], s[58:59], v[2:3] op_sel_hi:[1,0,1]
	v_readlane_b32 s56, v193, 50
	v_readlane_b32 s58, v193, 51
	s_waitcnt vmcnt(14)
	v_pk_fma_f32 v[8:9], v[140:141], s[52:53], v[8:9] op_sel_hi:[1,0,1]
	v_pk_fma_f32 v[2:3], v[142:143], s[52:53], v[2:3] op_sel_hi:[1,0,1]
	v_pk_fma_f32 v[8:9], v[144:145], s[54:55], v[8:9] op_sel_hi:[1,0,1]
	v_pk_fma_f32 v[2:3], v[146:147], s[54:55], v[2:3] op_sel_hi:[1,0,1]
	v_readlane_b32 s52, v193, 52
	v_readlane_b32 s54, v193, 53
	s_waitcnt vmcnt(12)
	v_pk_fma_f32 v[8:9], v[148:149], s[56:57], v[8:9] op_sel_hi:[1,0,1]
	v_pk_fma_f32 v[2:3], v[150:151], s[56:57], v[2:3] op_sel_hi:[1,0,1]
	v_pk_fma_f32 v[8:9], v[152:153], s[58:59], v[8:9] op_sel_hi:[1,0,1]
	v_pk_fma_f32 v[2:3], v[154:155], s[58:59], v[2:3] op_sel_hi:[1,0,1]
	v_readlane_b32 s56, v193, 54
	v_readlane_b32 s58, v193, 55
	s_waitcnt vmcnt(10)
	v_pk_fma_f32 v[8:9], v[156:157], s[52:53], v[8:9] op_sel_hi:[1,0,1]
	v_pk_fma_f32 v[2:3], v[158:159], s[52:53], v[2:3] op_sel_hi:[1,0,1]
	v_pk_fma_f32 v[8:9], v[160:161], s[54:55], v[8:9] op_sel_hi:[1,0,1]
	v_pk_fma_f32 v[2:3], v[162:163], s[54:55], v[2:3] op_sel_hi:[1,0,1]
	v_readlane_b32 s52, v193, 56
	v_readlane_b32 s54, v193, 57
	s_waitcnt vmcnt(8)
	v_pk_fma_f32 v[8:9], v[164:165], s[56:57], v[8:9] op_sel_hi:[1,0,1]
	v_pk_fma_f32 v[2:3], v[166:167], s[56:57], v[2:3] op_sel_hi:[1,0,1]
	v_pk_fma_f32 v[8:9], v[168:169], s[58:59], v[8:9] op_sel_hi:[1,0,1]
	v_pk_fma_f32 v[2:3], v[170:171], s[58:59], v[2:3] op_sel_hi:[1,0,1]
	v_readlane_b32 s56, v193, 58
	v_readlane_b32 s58, v193, 59
	s_waitcnt vmcnt(6)
	v_pk_fma_f32 v[8:9], v[172:173], s[52:53], v[8:9] op_sel_hi:[1,0,1]
	v_pk_fma_f32 v[2:3], v[174:175], s[52:53], v[2:3] op_sel_hi:[1,0,1]
	v_pk_fma_f32 v[8:9], v[176:177], s[54:55], v[8:9] op_sel_hi:[1,0,1]
	v_pk_fma_f32 v[2:3], v[178:179], s[54:55], v[2:3] op_sel_hi:[1,0,1]
	v_readlane_b32 s52, v193, 60
	v_readlane_b32 s54, v193, 61
	s_waitcnt vmcnt(4)
	v_pk_fma_f32 v[8:9], v[180:181], s[56:57], v[8:9] op_sel_hi:[1,0,1]
	v_pk_fma_f32 v[2:3], v[182:183], s[56:57], v[2:3] op_sel_hi:[1,0,1]
	v_pk_fma_f32 v[8:9], v[184:185], s[58:59], v[8:9] op_sel_hi:[1,0,1]
	v_pk_fma_f32 v[2:3], v[186:187], s[58:59], v[2:3] op_sel_hi:[1,0,1]
	v_readlane_b32 s56, v193, 62
	v_readlane_b32 s58, v193, 63
	s_waitcnt vmcnt(2)
	v_pk_fma_f32 v[8:9], v[188:189], s[52:53], v[8:9] op_sel_hi:[1,0,1]
	v_pk_fma_f32 v[2:3], v[190:191], s[52:53], v[2:3] op_sel_hi:[1,0,1]
	v_pk_fma_f32 v[8:9], v[198:199], s[54:55], v[8:9] op_sel_hi:[1,0,1]
	v_pk_fma_f32 v[2:3], v[200:201], s[54:55], v[2:3] op_sel_hi:[1,0,1]
	s_waitcnt vmcnt(0)
	v_pk_fma_f32 v[8:9], v[202:203], s[56:57], v[8:9] op_sel_hi:[1,0,1]
	v_pk_fma_f32 v[2:3], v[204:205], s[56:57], v[2:3] op_sel_hi:[1,0,1]
	v_pk_fma_f32 v[8:9], v[206:207], s[58:59], v[8:9] op_sel_hi:[1,0,1]
	v_pk_fma_f32 v[2:3], v[208:209], s[58:59], v[2:3] op_sel_hi:[1,0,1]
	v_lshlrev_b32_e32 v6, 2, v13
	v_and_b32_e32 v6, 0x60, v6
	v_lshlrev_b32_e32 v14, 4, v13
	v_lshrrev_b32_e32 v7, 8, v13
	v_and_or_b32 v6, v14, 16, v6
	v_lshrrev_b32_e32 v4, 3, v13
	v_bfe_u32 v10, v8, 16, 1
	v_lshrrev_b32_e32 v6, 3, v6
	v_bfe_u32 v7, v7, 5, 1
	v_and_b32_e32 v4, 24, v4
	v_ashrrev_i32_e32 v5, 14, v13
	v_add3_u32 v8, v8, v10, s81
	v_bfe_u32 v10, v13, 8, 6
	v_or_b32_e32 v6, v6, v7
	v_add_u32_e32 v4, v4, v5
	v_lshlrev_b32_e32 v14, 7, v13
	v_lshlrev_b32_e32 v10, 1, v10
	v_lshlrev_b32_e32 v16, 10, v6
	v_lshlrev_b32_e32 v6, 3, v13
	v_ashrrev_i32_e32 v5, 31, v4
	v_lshlrev_b32_e32 v11, 9, v13
	v_or_b32_e32 v7, v14, v10
	v_and_b32_e32 v17, 32, v6
	v_lshlrev_b64 v[4:5], 15, v[4:5]
	v_and_b32_e32 v11, 0x4000, v11
	v_bitop3_b32 v6, v7, v17, s83 bitop3:0x6c
	v_lshl_add_u64 v[4:5], s[20:21], 0, v[4:5]
	v_or3_b32 v6, v11, v6, v16
	v_mov_b32_e32 v7, v67
	v_lshl_add_u64 v[6:7], v[4:5], 0, v[6:7]
	global_store_short_d16_hi v[6:7], v8, off
	v_bfe_u32 v6, v9, 16, 1
	s_movk_i32 s2, 0x300
	v_add3_u32 v8, v9, v6, s81
	v_and_or_b32 v9, v14, s2, v10
	v_bitop3_b32 v6, v9, v17, 64 bitop3:0x36
	v_or3_b32 v6, v11, v6, v16
	v_mov_b32_e32 v7, v67
	v_lshl_add_u64 v[6:7], v[4:5], 0, v[6:7]
	v_bitop3_b32 v15, v14, s83, v10 bitop3:0xc8
	global_store_short_d16_hi v[6:7], v8, off
	v_bfe_u32 v6, v2, 16, 1
	s_movk_i32 s2, 0x80
	v_add3_u32 v2, v2, v6, s81
	v_bitop3_b32 v6, v15, v17, s2 bitop3:0x36
	v_or3_b32 v6, v11, v6, v16
	v_mov_b32_e32 v7, v67
	v_lshl_add_u64 v[6:7], v[4:5], 0, v[6:7]
	global_store_short_d16_hi v[6:7], v2, off
	v_bfe_u32 v2, v3, 16, 1
	v_add3_u32 v6, v3, v2, s81
	v_bitop3_b32 v2, v9, v17, s16 bitop3:0x36
	v_add_u32_e32 v13, s93, v13
	v_or3_b32 v2, v11, v2, v16
	v_mov_b32_e32 v3, v67
	v_cmp_lt_i32_e32 vcc, s94, v13
	v_lshl_add_u64 v[2:3], v[4:5], 0, v[2:3]
	s_or_b64 s[14:15], vcc, s[14:15]
	v_add_u32_e32 v12, s80, v12
	global_store_short_d16_hi v[2:3], v6, off
	s_andn2_b64 exec, exec, s[14:15]
	s_cbranch_execnz .LBB0_15
	s_or_b64 exec, exec, s[14:15]
	s_mov_b64 s[14:15], 0
	v_mov_b32_e32 v6, v86
	s_branch .LBB0_20
